# SWA epilogue: lane^1 exchange by DPP quad_perm instead of ds_bpermute, 16 row-sum LDS reads batched (on top of v30)
# baseline (speedup 1.0000x reference)
; __device__ __forceinline__ int crow(int r, int hi) { return (r & 3) + 8 * (r >> 2) + 4 * hi; }
; __device__ __forceinline__ unsigned cvtpk(float lo, float hi) { f32x2_cv v = {lo, hi}; bf16x2_cv b = __builtin_convertvector(v, bf16x2_cv); return __builtin_bit_cast(unsigned, b); }
; template <bool MLA> __device__ __forceinline__ void attn_unit(const AttnP& P, int b, int hh, int qb, LAS char* lds) {
;     ...
;     if (hi == 0) li_l[r32] = l_reg; asm volatile("s_waitcnt lgkmcnt(0)" ::: "memory");
;     bf16_t* Ow = (MLA ? P.QN + (rowbase + qlo) * 2048 + hh * 128 : P.QS + (rowbase + qlo) * 2048 + hh * 64);
; #pragma unroll
;     for (int r = 0; r < 16; ++r) { const int orow = crow(r, hi); const float rl = __builtin_amdgcn_rcpf(li_l[orow]);
; #pragma unroll
;         for (int d0 = 0; d0 < NCB; ++d0) { const float v = o[d0][r] * rl; const float vn = __shfl_xor(v, 1);
;             if ((r32 & 1) == 0) *(unsigned*)(Ow + (size_t)orow * 2048 + d0 * 32 + r32) = cvtpk(v, vn); } }
.LBB0_616:
	s_and_saveexec_b64 s[48:49], s[6:7]
	ds_write_b32 v131, v152 offset:32768
	s_or_b64 exec, exec, s[48:49]
	s_waitcnt lgkmcnt(0)
	ds_read_b32 v182, v133 offset:32768
	ds_read_b32 v183, v133 offset:32772
	ds_read_b32 v184, v133 offset:32776
	ds_read_b32 v185, v133 offset:32780
	ds_read_b32 v186, v133 offset:32800
	ds_read_b32 v187, v133 offset:32804
	ds_read_b32 v188, v133 offset:32808
	ds_read_b32 v189, v133 offset:32812
	ds_read_b32 v190, v133 offset:32832
	ds_read_b32 v191, v133 offset:32836
	ds_read_b32 v192, v133 offset:32840
	ds_read_b32 v193, v133 offset:32844
	ds_read_b32 v194, v133 offset:32864
	ds_read_b32 v195, v133 offset:32868
	ds_read_b32 v196, v133 offset:32872
	ds_read_b32 v197, v133 offset:32876
	s_waitcnt lgkmcnt(0)
	v_mov_b32_e32 v34, v182
	v_and_b32_e32 v36, 64, v149
	v_xor_b32_e32 v35, 1, v149
	v_add_u32_e32 v36, 64, v36
	v_cmp_lt_i32_e32 vcc, v35, v36
	s_waitcnt lgkmcnt(0)
	v_rcp_f32_e32 v39, v34
	s_lshl_b64 s[16:17], s[46:47], 12
	v_cndmask_b32_e32 v34, v149, v35, vcc
	s_add_u32 s13, s18, s16
	v_lshlrev_b32_e32 v38, 2, v34
	v_mul_f32_e32 v18, v18, v39
	s_addc_u32 s15, s19, s17
	s_lshl_b32 s14, s14, 1
	s_nop 1
	v_mov_b32_dpp v40, v18 quad_perm:[1,0,3,2] row_mask:0xf bank_mask:0xf
	s_add_u32 s14, s13, s14
	s_addc_u32 s15, s15, 0
	v_mov_b32_e32 v131, v93
	v_lshl_add_u64 v[34:35], s[14:15], 0, v[130:131]
	v_lshl_add_u64 v[36:37], v[34:35], 0, v[98:99]
	s_and_saveexec_b64 s[46:47], s[4:5]
	s_cbranch_execz .LBB0_620
	s_waitcnt lgkmcnt(0)
	v_cvt_pk_bf16_f32 v18, v18, v40
	global_store_dword v[36:37], v18, off
.LBB0_620:
	s_or_b64 exec, exec, s[46:47]
	v_mul_f32_e32 v2, v2, v39
	s_nop 1
	v_mov_b32_dpp v18, v2 quad_perm:[1,0,3,2] row_mask:0xf bank_mask:0xf
	s_and_saveexec_b64 s[46:47], s[4:5]
	s_cbranch_execz .LBB0_622
	s_waitcnt lgkmcnt(0)
	v_cvt_pk_bf16_f32 v2, v2, v18
	global_store_dword v[36:37], v2, off offset:64
.LBB0_622:
	s_or_b64 exec, exec, s[46:47]
	v_mov_b32_e32 v2, v183
	s_waitcnt lgkmcnt(0)
	v_rcp_f32_e32 v2, v2
	s_nop 0
	v_mul_f32_e32 v36, v19, v2
	s_nop 1
	v_mov_b32_dpp v37, v36 quad_perm:[1,0,3,2] row_mask:0xf bank_mask:0xf
	v_lshl_add_u64 v[18:19], v[34:35], 0, v[100:101]
	s_and_saveexec_b64 s[46:47], s[4:5]
	s_cbranch_execz .LBB0_624
	s_waitcnt lgkmcnt(0)
	v_cvt_pk_bf16_f32 v36, v36, v37
	global_store_dword v[18:19], v36, off
.LBB0_624:
	s_or_b64 exec, exec, s[46:47]
	v_mul_f32_e32 v2, v3, v2
	s_nop 1
	v_mov_b32_dpp v3, v2 quad_perm:[1,0,3,2] row_mask:0xf bank_mask:0xf
	s_and_saveexec_b64 s[46:47], s[4:5]
	s_cbranch_execz .LBB0_626
	s_waitcnt lgkmcnt(0)
	v_cvt_pk_bf16_f32 v2, v2, v3
	global_store_dword v[18:19], v2, off offset:64
.LBB0_626:
	s_or_b64 exec, exec, s[46:47]
	v_mov_b32_e32 v2, v184
	s_waitcnt lgkmcnt(0)
	v_rcp_f32_e32 v18, v2
	v_lshl_add_u64 v[2:3], v[34:35], 0, v[102:103]
	v_mul_f32_e32 v19, v20, v18
	s_nop 1
	v_mov_b32_dpp v20, v19 quad_perm:[1,0,3,2] row_mask:0xf bank_mask:0xf
	s_and_saveexec_b64 s[46:47], s[4:5]
	s_cbranch_execz .LBB0_628
	s_waitcnt lgkmcnt(0)
	v_cvt_pk_bf16_f32 v19, v19, v20
	global_store_dword v[2:3], v19, off
.LBB0_628:
	s_or_b64 exec, exec, s[46:47]
	v_mul_f32_e32 v4, v4, v18
	s_nop 1
	v_mov_b32_dpp v18, v4 quad_perm:[1,0,3,2] row_mask:0xf bank_mask:0xf
	s_and_saveexec_b64 s[46:47], s[4:5]
	s_cbranch_execz .LBB0_630
	s_waitcnt lgkmcnt(0)
	v_cvt_pk_bf16_f32 v4, v4, v18
	global_store_dword v[2:3], v4, off offset:64
.LBB0_630:
	s_or_b64 exec, exec, s[46:47]
	v_mov_b32_e32 v2, v185
	s_waitcnt lgkmcnt(0)
	v_rcp_f32_e32 v4, v2
	v_lshl_add_u64 v[2:3], v[34:35], 0, v[104:105]
	v_mul_f32_e32 v18, v21, v4
	s_nop 1
	v_mov_b32_dpp v19, v18 quad_perm:[1,0,3,2] row_mask:0xf bank_mask:0xf
	s_and_saveexec_b64 s[46:47], s[4:5]
	s_cbranch_execz .LBB0_632
	s_waitcnt lgkmcnt(0)
	v_cvt_pk_bf16_f32 v18, v18, v19
	global_store_dword v[2:3], v18, off
.LBB0_632:
	s_or_b64 exec, exec, s[46:47]
	v_mul_f32_e32 v4, v5, v4
	s_nop 1
	v_mov_b32_dpp v5, v4 quad_perm:[1,0,3,2] row_mask:0xf bank_mask:0xf
	s_and_saveexec_b64 s[46:47], s[4:5]
	s_cbranch_execz .LBB0_634
	s_waitcnt lgkmcnt(0)
	v_cvt_pk_bf16_f32 v4, v4, v5
	global_store_dword v[2:3], v4, off offset:64
.LBB0_634:
	s_or_b64 exec, exec, s[46:47]
	v_mov_b32_e32 v2, v186
	s_waitcnt lgkmcnt(0)
	v_rcp_f32_e32 v4, v2
	v_lshl_add_u64 v[2:3], v[34:35], 0, v[106:107]
	v_mul_f32_e32 v5, v22, v4
	s_nop 1
	v_mov_b32_dpp v18, v5 quad_perm:[1,0,3,2] row_mask:0xf bank_mask:0xf
	s_and_saveexec_b64 s[46:47], s[4:5]
	s_cbranch_execz .LBB0_636
	s_waitcnt lgkmcnt(0)
	v_cvt_pk_bf16_f32 v5, v5, v18
	global_store_dword v[2:3], v5, off
.LBB0_636:
	s_or_b64 exec, exec, s[46:47]
	v_mul_f32_e32 v4, v6, v4
	s_nop 1
	v_mov_b32_dpp v5, v4 quad_perm:[1,0,3,2] row_mask:0xf bank_mask:0xf
	s_and_saveexec_b64 s[46:47], s[4:5]
	s_cbranch_execz .LBB0_638
	s_waitcnt lgkmcnt(0)
	v_cvt_pk_bf16_f32 v4, v4, v5
	global_store_dword v[2:3], v4, off offset:64
.LBB0_638:
	s_or_b64 exec, exec, s[46:47]
	v_mov_b32_e32 v2, v187
	s_waitcnt lgkmcnt(0)
	v_rcp_f32_e32 v4, v2
	v_lshl_add_u64 v[2:3], v[34:35], 0, v[108:109]
	v_mul_f32_e32 v5, v23, v4
	s_nop 1
	v_mov_b32_dpp v6, v5 quad_perm:[1,0,3,2] row_mask:0xf bank_mask:0xf
	s_and_saveexec_b64 s[46:47], s[4:5]
	s_cbranch_execz .LBB0_640
	s_waitcnt lgkmcnt(0)
	v_cvt_pk_bf16_f32 v5, v5, v6
	global_store_dword v[2:3], v5, off
.LBB0_640:
	s_or_b64 exec, exec, s[46:47]
	v_mul_f32_e32 v4, v7, v4
	s_nop 1
	v_mov_b32_dpp v5, v4 quad_perm:[1,0,3,2] row_mask:0xf bank_mask:0xf
	s_and_saveexec_b64 s[46:47], s[4:5]
	s_cbranch_execz .LBB0_642
	s_waitcnt lgkmcnt(0)
	v_cvt_pk_bf16_f32 v4, v4, v5
	global_store_dword v[2:3], v4, off offset:64
; __device__ __forceinline__ int crow(int r, int hi) { return (r & 3) + 8 * (r >> 2) + 4 * hi; }
; __device__ __forceinline__ unsigned cvtpk(float lo, float hi) { f32x2_cv v = {lo, hi}; bf16x2_cv b = __builtin_convertvector(v, bf16x2_cv); return __builtin_bit_cast(unsigned, b); }
; template <bool MLA> __device__ __forceinline__ void attn_unit(const AttnP& P, int b, int hh, int qb, LAS char* lds) {
;     ...
;     for (int r = 0; r < 16; ++r) { const int orow = crow(r, hi); const float rl = __builtin_amdgcn_rcpf(li_l[orow]);
; #pragma unroll
;         for (int d0 = 0; d0 < NCB; ++d0) { const float v = o[d0][r] * rl; const float vn = __shfl_xor(v, 1);
;             if ((r32 & 1) == 0) *(unsigned*)(Ow + (size_t)orow * 2048 + d0 * 32 + r32) = cvtpk(v, vn); } }
.LBB0_642:
	s_or_b64 exec, exec, s[46:47]
	v_mov_b32_e32 v2, v188
	s_waitcnt lgkmcnt(0)
	v_rcp_f32_e32 v4, v2
	v_lshl_add_u64 v[2:3], v[34:35], 0, v[110:111]
	v_mul_f32_e32 v5, v24, v4
	s_nop 1
	v_mov_b32_dpp v6, v5 quad_perm:[1,0,3,2] row_mask:0xf bank_mask:0xf
	s_and_saveexec_b64 s[46:47], s[4:5]
	s_cbranch_execz .LBB0_644
	s_waitcnt lgkmcnt(0)
	v_cvt_pk_bf16_f32 v5, v5, v6
	global_store_dword v[2:3], v5, off
.LBB0_644:
	s_or_b64 exec, exec, s[46:47]
	v_mul_f32_e32 v4, v8, v4
	s_nop 1
	v_mov_b32_dpp v5, v4 quad_perm:[1,0,3,2] row_mask:0xf bank_mask:0xf
	s_and_saveexec_b64 s[46:47], s[4:5]
	s_cbranch_execz .LBB0_646
	s_waitcnt lgkmcnt(0)
	v_cvt_pk_bf16_f32 v4, v4, v5
	global_store_dword v[2:3], v4, off offset:64
.LBB0_646:
	s_or_b64 exec, exec, s[46:47]
	v_mov_b32_e32 v2, v189
	s_waitcnt lgkmcnt(0)
	v_rcp_f32_e32 v4, v2
	v_lshl_add_u64 v[2:3], v[34:35], 0, v[112:113]
	v_mul_f32_e32 v5, v25, v4
	s_nop 1
	v_mov_b32_dpp v6, v5 quad_perm:[1,0,3,2] row_mask:0xf bank_mask:0xf
	s_and_saveexec_b64 s[46:47], s[4:5]
	s_cbranch_execz .LBB0_648
	s_waitcnt lgkmcnt(0)
	v_cvt_pk_bf16_f32 v5, v5, v6
	global_store_dword v[2:3], v5, off
.LBB0_648:
	s_or_b64 exec, exec, s[46:47]
	v_mul_f32_e32 v4, v9, v4
	s_nop 1
	v_mov_b32_dpp v5, v4 quad_perm:[1,0,3,2] row_mask:0xf bank_mask:0xf
	s_and_saveexec_b64 s[46:47], s[4:5]
	s_cbranch_execz .LBB0_650
	s_waitcnt lgkmcnt(0)
	v_cvt_pk_bf16_f32 v4, v4, v5
	global_store_dword v[2:3], v4, off offset:64
.LBB0_650:
	s_or_b64 exec, exec, s[46:47]
	v_mov_b32_e32 v2, v190
	s_waitcnt lgkmcnt(0)
	v_rcp_f32_e32 v4, v2
	v_lshl_add_u64 v[2:3], v[34:35], 0, v[114:115]
	v_mul_f32_e32 v5, v26, v4
	s_nop 1
	v_mov_b32_dpp v6, v5 quad_perm:[1,0,3,2] row_mask:0xf bank_mask:0xf
	s_and_saveexec_b64 s[46:47], s[4:5]
	s_cbranch_execz .LBB0_652
	s_waitcnt lgkmcnt(0)
	v_cvt_pk_bf16_f32 v5, v5, v6
	global_store_dword v[2:3], v5, off
.LBB0_652:
	s_or_b64 exec, exec, s[46:47]
	v_mul_f32_e32 v4, v10, v4
	s_nop 1
	v_mov_b32_dpp v5, v4 quad_perm:[1,0,3,2] row_mask:0xf bank_mask:0xf
	s_and_saveexec_b64 s[46:47], s[4:5]
	s_cbranch_execz .LBB0_654
	s_waitcnt lgkmcnt(0)
	v_cvt_pk_bf16_f32 v4, v4, v5
	global_store_dword v[2:3], v4, off offset:64
.LBB0_654:
	s_or_b64 exec, exec, s[46:47]
	v_mov_b32_e32 v2, v191
	s_waitcnt lgkmcnt(0)
	v_rcp_f32_e32 v4, v2
	v_lshl_add_u64 v[2:3], v[34:35], 0, v[116:117]
	v_mul_f32_e32 v5, v27, v4
	s_nop 1
	v_mov_b32_dpp v6, v5 quad_perm:[1,0,3,2] row_mask:0xf bank_mask:0xf
	s_and_saveexec_b64 s[46:47], s[4:5]
	s_cbranch_execz .LBB0_656
	s_waitcnt lgkmcnt(0)
	v_cvt_pk_bf16_f32 v5, v5, v6
	global_store_dword v[2:3], v5, off
.LBB0_656:
	s_or_b64 exec, exec, s[46:47]
	v_mul_f32_e32 v4, v11, v4
	s_nop 1
	v_mov_b32_dpp v5, v4 quad_perm:[1,0,3,2] row_mask:0xf bank_mask:0xf
	s_and_saveexec_b64 s[46:47], s[4:5]
	s_cbranch_execz .LBB0_658
	s_waitcnt lgkmcnt(0)
	v_cvt_pk_bf16_f32 v4, v4, v5
	global_store_dword v[2:3], v4, off offset:64
.LBB0_658:
	s_or_b64 exec, exec, s[46:47]
	v_mov_b32_e32 v2, v192
	s_waitcnt lgkmcnt(0)
	v_rcp_f32_e32 v4, v2
	v_lshl_add_u64 v[2:3], v[34:35], 0, v[118:119]
	v_mul_f32_e32 v5, v28, v4
	s_nop 1
	v_mov_b32_dpp v6, v5 quad_perm:[1,0,3,2] row_mask:0xf bank_mask:0xf
	s_and_saveexec_b64 s[46:47], s[4:5]
	s_cbranch_execz .LBB0_660
	s_waitcnt lgkmcnt(0)
	v_cvt_pk_bf16_f32 v5, v5, v6
	global_store_dword v[2:3], v5, off
.LBB0_660:
	s_or_b64 exec, exec, s[46:47]
	v_mul_f32_e32 v4, v12, v4
	s_nop 1
	v_mov_b32_dpp v5, v4 quad_perm:[1,0,3,2] row_mask:0xf bank_mask:0xf
	s_and_saveexec_b64 s[46:47], s[4:5]
	s_cbranch_execz .LBB0_662
	s_waitcnt lgkmcnt(0)
	v_cvt_pk_bf16_f32 v4, v4, v5
	global_store_dword v[2:3], v4, off offset:64
; __device__ __forceinline__ int crow(int r, int hi) { return (r & 3) + 8 * (r >> 2) + 4 * hi; }
; __device__ __forceinline__ unsigned cvtpk(float lo, float hi) { f32x2_cv v = {lo, hi}; bf16x2_cv b = __builtin_convertvector(v, bf16x2_cv); return __builtin_bit_cast(unsigned, b); }
; template <bool MLA> __device__ __forceinline__ void attn_unit(const AttnP& P, int b, int hh, int qb, LAS char* lds) {
;     ...
;     for (int r = 0; r < 16; ++r) { const int orow = crow(r, hi); const float rl = __builtin_amdgcn_rcpf(li_l[orow]);
; #pragma unroll
;         for (int d0 = 0; d0 < NCB; ++d0) { const float v = o[d0][r] * rl; const float vn = __shfl_xor(v, 1);
;             if ((r32 & 1) == 0) *(unsigned*)(Ow + (size_t)orow * 2048 + d0 * 32 + r32) = cvtpk(v, vn); } }
.LBB0_662:
	s_or_b64 exec, exec, s[46:47]
	v_mov_b32_e32 v2, v193
	s_waitcnt lgkmcnt(0)
	v_rcp_f32_e32 v4, v2
	v_lshl_add_u64 v[2:3], v[34:35], 0, v[120:121]
	v_mul_f32_e32 v5, v29, v4
	s_nop 1
	v_mov_b32_dpp v6, v5 quad_perm:[1,0,3,2] row_mask:0xf bank_mask:0xf
	s_and_saveexec_b64 s[46:47], s[4:5]
	s_cbranch_execz .LBB0_664
	s_waitcnt lgkmcnt(0)
	v_cvt_pk_bf16_f32 v5, v5, v6
	global_store_dword v[2:3], v5, off
.LBB0_664:
	s_or_b64 exec, exec, s[46:47]
	v_mul_f32_e32 v4, v13, v4
	s_nop 1
	v_mov_b32_dpp v5, v4 quad_perm:[1,0,3,2] row_mask:0xf bank_mask:0xf
	s_and_saveexec_b64 s[46:47], s[4:5]
	s_cbranch_execz .LBB0_666
	s_waitcnt lgkmcnt(0)
	v_cvt_pk_bf16_f32 v4, v4, v5
	global_store_dword v[2:3], v4, off offset:64
.LBB0_666:
	s_or_b64 exec, exec, s[46:47]
	v_mov_b32_e32 v2, v194
	s_waitcnt lgkmcnt(0)
	v_rcp_f32_e32 v4, v2
	v_lshl_add_u64 v[2:3], v[34:35], 0, v[122:123]
	v_mul_f32_e32 v5, v30, v4
	s_nop 1
	v_mov_b32_dpp v6, v5 quad_perm:[1,0,3,2] row_mask:0xf bank_mask:0xf
	s_and_saveexec_b64 s[46:47], s[4:5]
	s_cbranch_execz .LBB0_668
	s_waitcnt lgkmcnt(0)
	v_cvt_pk_bf16_f32 v5, v5, v6
	global_store_dword v[2:3], v5, off
.LBB0_668:
	s_or_b64 exec, exec, s[46:47]
	v_mul_f32_e32 v4, v14, v4
	s_nop 1
	v_mov_b32_dpp v5, v4 quad_perm:[1,0,3,2] row_mask:0xf bank_mask:0xf
	s_and_saveexec_b64 s[46:47], s[4:5]
	s_cbranch_execz .LBB0_670
	s_waitcnt lgkmcnt(0)
	v_cvt_pk_bf16_f32 v4, v4, v5
	global_store_dword v[2:3], v4, off offset:64
.LBB0_670:
	s_or_b64 exec, exec, s[46:47]
	v_mov_b32_e32 v2, v195
	s_waitcnt lgkmcnt(0)
	v_rcp_f32_e32 v4, v2
	v_lshl_add_u64 v[2:3], v[34:35], 0, v[124:125]
	v_mul_f32_e32 v5, v31, v4
	s_nop 1
	v_mov_b32_dpp v6, v5 quad_perm:[1,0,3,2] row_mask:0xf bank_mask:0xf
	s_and_saveexec_b64 s[46:47], s[4:5]
	s_cbranch_execz .LBB0_672
	s_waitcnt lgkmcnt(0)
	v_cvt_pk_bf16_f32 v5, v5, v6
	global_store_dword v[2:3], v5, off
.LBB0_672:
	s_or_b64 exec, exec, s[46:47]
	v_mul_f32_e32 v4, v15, v4
	s_nop 1
	v_mov_b32_dpp v5, v4 quad_perm:[1,0,3,2] row_mask:0xf bank_mask:0xf
	s_and_saveexec_b64 s[46:47], s[4:5]
	s_cbranch_execz .LBB0_674
	s_waitcnt lgkmcnt(0)
	v_cvt_pk_bf16_f32 v4, v4, v5
	global_store_dword v[2:3], v4, off offset:64
.LBB0_674:
	s_or_b64 exec, exec, s[46:47]
	v_mov_b32_e32 v2, v196
	s_waitcnt lgkmcnt(0)
	v_rcp_f32_e32 v4, v2
	v_lshl_add_u64 v[2:3], v[34:35], 0, v[126:127]
	v_mul_f32_e32 v5, v32, v4
	s_nop 1
	v_mov_b32_dpp v6, v5 quad_perm:[1,0,3,2] row_mask:0xf bank_mask:0xf
	s_and_saveexec_b64 s[46:47], s[4:5]
	s_cbranch_execz .LBB0_676
	s_waitcnt lgkmcnt(0)
	v_cvt_pk_bf16_f32 v5, v5, v6
	global_store_dword v[2:3], v5, off
.LBB0_676:
	s_or_b64 exec, exec, s[46:47]
	v_mul_f32_e32 v4, v16, v4
	s_nop 1
	v_mov_b32_dpp v5, v4 quad_perm:[1,0,3,2] row_mask:0xf bank_mask:0xf
	s_and_saveexec_b64 s[46:47], s[4:5]
	s_cbranch_execz .LBB0_678
	s_waitcnt lgkmcnt(0)
	v_cvt_pk_bf16_f32 v4, v4, v5
	global_store_dword v[2:3], v4, off offset:64
.LBB0_678:
	s_or_b64 exec, exec, s[46:47]
	v_mov_b32_e32 v2, v197
	s_waitcnt lgkmcnt(0)
	v_rcp_f32_e32 v4, v2
	v_lshl_add_u64 v[2:3], v[34:35], 0, v[128:129]
	v_mul_f32_e32 v5, v33, v4
	s_nop 1
	v_mov_b32_dpp v6, v5 quad_perm:[1,0,3,2] row_mask:0xf bank_mask:0xf
	s_and_saveexec_b64 s[46:47], s[4:5]
	s_cbranch_execz .LBB0_680
	s_waitcnt lgkmcnt(0)
	v_cvt_pk_bf16_f32 v5, v5, v6
	global_store_dword v[2:3], v5, off
.LBB0_680:
	s_or_b64 exec, exec, s[46:47]
	v_mul_f32_e32 v4, v17, v4
	s_nop 1
	v_mov_b32_dpp v5, v4 quad_perm:[1,0,3,2] row_mask:0xf bank_mask:0xf
	s_and_saveexec_b64 s[46:47], s[4:5]
	s_cbranch_execz .LBB0_599
	s_waitcnt lgkmcnt(0)
	v_cvt_pk_bf16_f32 v4, v4, v5
	global_store_dword v[2:3], v4, off offset:64
	s_branch .LBB0_599
